# diff-attention pass-2 epilogue: guard load and sub-LN gain loads issued ahead of the scratch read-back
# baseline (speedup 1.0000x reference)
; template <int THRL> ...
;     ...
;         for (int r = 0; r < 16; r += 2) { const unsigned w = ((const unsigned*)scr)[(d0 * 8 + (r >> 1)) * 64];
;           const float v0 = __uint_as_float(w << 16) - lam * (o[d0][r] * rli[r]), v1 = __uint_as_float(w & 0xffff0000u) - lam * (o[d0][r + 1] * rli[r + 1]);
;           o[d0][r] = v0; o[d0][r + 1] = v1; ss[r] += v0 * v0; ss[r + 1] += v1 * v1; }
;     ...
;       const unsigned gd_ = need ? __hip_atomic_load(guard, __ATOMIC_RELAXED, __HIP_MEMORY_SCOPE_AGENT) : 0u;
;       float g[4];
; #pragma unroll
;       for (int d0 = 0; d0 < 4; ++d0) g[d0] = subg[d0 * 32 + r32_o];
.LBB0_481:
	global_load_dword v244, v147, s[12:13] sc1
	v_mov_b32_e32 v250, v70
	v_ashrrev_i32_e32 v251, 31, v70
	v_lshl_add_u64 v[250:251], v[250:251], 2, s[22:23]
	global_load_dword v245, v[250:251], off
	global_load_dword v246, v[250:251], off offset:128
	global_load_dword v247, v[250:251], off offset:256
	global_load_dword v248, v[250:251], off offset:384
	global_load_dword v26, v[66:67], off
	global_load_dword v27, v[66:67], off offset:256
	global_load_dword v28, v[66:67], off offset:512
	global_load_dword v29, v[66:67], off offset:768
	global_load_dword v30, v[66:67], off offset:1024
	global_load_dword v31, v[66:67], off offset:1280
	global_load_dword v32, v[66:67], off offset:1536
	global_load_dword v33, v[66:67], off offset:1792
	global_load_dword v40, v[66:67], off offset:2048
	global_load_dword v41, v[66:67], off offset:2304
	global_load_dword v42, v[66:67], off offset:2560
	global_load_dword v44, v[66:67], off offset:2816
	global_load_dword v45, v[66:67], off offset:3072
	global_load_dword v71, v[66:67], off offset:3328
	global_load_dword v97, v[66:67], off offset:3584
	global_load_dword v100, v[66:67], off offset:3840
	v_add_co_u32_e32 v106, vcc, s78, v66
	s_mov_b64 s[28:29], 0
	s_nop 0
	v_addc_co_u32_e32 v107, vcc, 0, v67, vcc
	global_load_dword v103, v[106:107], off
	global_load_dword v109, v[106:107], off offset:256
	global_load_dword v110, v[106:107], off offset:512
	global_load_dword v111, v[106:107], off offset:768
	global_load_dword v112, v[106:107], off offset:1024
	global_load_dword v114, v[106:107], off offset:1280
	global_load_dword v209, v[106:107], off offset:3584
	s_and_b64 vcc, exec, s[4:5]
	global_load_dword v122, v[106:107], off offset:1792
	global_load_dword v126, v[106:107], off offset:2048
	global_load_dword v130, v[106:107], off offset:2304
	global_load_dword v133, v[106:107], off offset:2560
	global_load_dword v204, v[106:107], off offset:2816
	global_load_dword v205, v[106:107], off offset:3072
	global_load_dword v208, v[106:107], off offset:3328
	s_waitcnt vmcnt(29)
	v_lshlrev_b32_e32 v43, 16, v26
	v_and_b32_e32 v26, 0xffff0000, v26
	v_fma_f32 v102, -v186, v79, v26
	s_waitcnt vmcnt(28)
	v_lshlrev_b32_e32 v46, 16, v27
	s_waitcnt vmcnt(25)
	v_lshlrev_b32_e32 v49, 16, v30
	v_and_b32_e32 v30, 0xffff0000, v30
	s_waitcnt vmcnt(24)
	v_and_b32_e32 v65, 0xffff0000, v31
	s_waitcnt vmcnt(23)
	v_lshlrev_b32_e32 v93, 16, v32
	v_and_b32_e32 v95, 0xffff0000, v32
	v_fma_f32 v32, -v186, v83, v30
	v_fma_f32 v30, -v186, v84, v65
	s_waitcnt vmcnt(18)
	v_lshlrev_b32_e32 v118, 16, v44
	v_fma_f32 v65, -v186, v53, v118
	global_load_dword v118, v[106:107], off offset:1536
	v_lshlrev_b32_e32 v98, 16, v33
	global_load_dword v107, v[106:107], off offset:3840
	v_and_b32_e32 v33, 0xffff0000, v33
	v_lshlrev_b32_e32 v64, 16, v31
	v_fma_f32 v26, -v186, v86, v33
	v_and_b32_e32 v33, 0xffff0000, v44
	v_fma_f32 v31, -v186, v76, v64
	v_fma_f32 v64, -v186, v90, v33
	s_waitcnt vmcnt(19)
	v_lshlrev_b32_e32 v33, 16, v45
	v_lshlrev_b32_e32 v48, 16, v29
	v_lshlrev_b32_e32 v101, 16, v40
	v_and_b32_e32 v104, 0xffff0000, v40
	v_fma_f32 v40, -v186, v75, v49
	v_fma_f32 v49, -v186, v54, v33
	v_and_b32_e32 v33, 0xffff0000, v45
	v_lshlrev_b32_e32 v47, 16, v28
	v_fma_f32 v99, -v186, v72, v46
	v_fma_f32 v46, -v186, v74, v48
	v_fma_f32 v48, -v186, v59, v33
	s_waitcnt vmcnt(18)
	v_lshlrev_b32_e32 v33, 16, v71
	v_fma_f32 v94, -v186, v73, v47
	v_fma_f32 v47, -v186, v55, v33
	v_and_b32_e32 v33, 0xffff0000, v71
	v_fma_f32 v45, -v186, v60, v33
	s_waitcnt vmcnt(17)
	v_lshlrev_b32_e32 v33, 16, v97
	v_fma_f32 v44, -v186, v56, v33
	v_and_b32_e32 v33, 0xffff0000, v97
	s_waitcnt vmcnt(15)
	v_lshlrev_b32_e32 v97, 16, v103
	v_fma_f32 v138, -v186, v58, v97
	v_and_b32_e32 v97, 0xffff0000, v103
	v_fma_f32 v136, -v186, v63, v97
	s_waitcnt vmcnt(14)
	v_lshlrev_b32_e32 v97, 16, v109
	v_fma_f32 v134, -v186, v2, v97
	v_and_b32_e32 v97, 0xffff0000, v109
	v_fma_f32 v132, -v186, v17, v97
	s_waitcnt vmcnt(13)
	v_lshlrev_b32_e32 v97, 16, v110
	v_fma_f32 v131, -v186, v3, v97
	v_and_b32_e32 v97, 0xffff0000, v110
	v_fma_f32 v127, -v186, v34, v97
	s_waitcnt vmcnt(12)
	v_lshlrev_b32_e32 v97, 16, v111
	v_fma_f32 v123, -v186, v4, v97
	v_and_b32_e32 v97, 0xffff0000, v111
	v_and_b32_e32 v28, 0xffff0000, v28
	v_lshlrev_b32_e32 v115, 16, v42
	v_fma_f32 v119, -v186, v35, v97
	s_waitcnt vmcnt(11)
	v_lshlrev_b32_e32 v97, 16, v112
	v_lshlrev_b32_e32 v113, 16, v41
	v_fma_f32 v92, -v186, v81, v28
	v_fma_f32 v28, -v186, v85, v95
	v_fma_f32 v95, -v186, v52, v115
	v_fma_f32 v115, -v186, v5, v97
	v_and_b32_e32 v97, 0xffff0000, v112
	v_fma_f32 v108, -v186, v50, v101
	v_fma_f32 v101, -v186, v51, v113
	v_fma_f32 v113, -v186, v36, v97
	s_waitcnt vmcnt(10)
	v_lshlrev_b32_e32 v97, 16, v114
	v_fma_f32 v111, -v186, v6, v97
	v_and_b32_e32 v97, 0xffff0000, v114
	v_fma_f32 v109, -v186, v37, v97
	v_and_b32_e32 v29, 0xffff0000, v29
	v_and_b32_e32 v42, 0xffff0000, v42
	v_and_b32_e32 v27, 0xffff0000, v27
	v_and_b32_e32 v41, 0xffff0000, v41
	v_fma_f32 v105, -v186, v69, v43
	v_fma_f32 v43, -v186, v82, v29
	v_fma_f32 v29, -v186, v77, v93
	v_fma_f32 v93, -v186, v89, v42
	v_fma_f32 v42, -v186, v61, v33
	v_lshlrev_b32_e32 v33, 16, v100
	v_fma_f32 v96, -v186, v80, v27
	v_fma_f32 v27, -v186, v78, v98
	v_fma_f32 v98, -v186, v88, v41
	v_fma_f32 v41, -v186, v57, v33
	v_and_b32_e32 v33, 0xffff0000, v100
	v_fma_f32 v104, -v186, v87, v104
	v_fma_f32 v33, -v186, v62, v33
	v_mul_f32_e32 v142, v108, v108
	v_mul_f32_e32 v143, v104, v104
	s_waitcnt vmcnt(7)
	v_lshlrev_b32_e32 v110, 16, v126
	v_fma_f32 v146, -v186, v9, v110
	v_and_b32_e32 v110, 0xffff0000, v126
	v_fma_f32 v145, -v186, v18, v110
	s_waitcnt vmcnt(6)
; template <int THRL> ...
;     ...
;         for (int r = 0; r < 16; r += 2) { const unsigned w = ((const unsigned*)scr)[(d0 * 8 + (r >> 1)) * 64];
;           const float v0 = __uint_as_float(w << 16) - lam * (o[d0][r] * rli[r]), v1 = __uint_as_float(w & 0xffff0000u) - lam * (o[d0][r + 1] * rli[r + 1]);
;           o[d0][r] = v0; o[d0][r + 1] = v1; ss[r] += v0 * v0; ss[r + 1] += v1 * v1; }
; #pragma unroll
;       for (int m_ = 1; m_ < 32; m_ <<= 1) {
;         float t_[16];
; #pragma unroll
;         for (int r = 0; r < 16; ++r) t_[r] = __shfl_xor(ss[r], m_);
; #pragma unroll
;         for (int r = 0; r < 16; ++r) ss[r] += t_[r];
;       }
	v_lshlrev_b32_e32 v110, 16, v130
	v_fma_f32 v141, -v186, v10, v110
	v_and_b32_e32 v110, 0xffff0000, v130
	v_fma_f32 v140, -v186, v19, v110
	s_waitcnt vmcnt(5)
	v_lshlrev_b32_e32 v110, 16, v133
	v_fma_f32 v139, -v186, v11, v110
	v_and_b32_e32 v110, 0xffff0000, v133
	v_fma_f32 v137, -v186, v20, v110
	s_waitcnt vmcnt(4)
	v_lshlrev_b32_e32 v110, 16, v204
	v_fma_f32 v135, -v186, v12, v110
	v_and_b32_e32 v110, 0xffff0000, v204
	s_waitcnt vmcnt(1)
	v_lshlrev_b32_e32 v97, 16, v118
	v_fma_f32 v133, -v186, v21, v110
	v_lshlrev_b32_e32 v110, 16, v205
	v_fma_f32 v106, -v186, v7, v97
	v_and_b32_e32 v97, 0xffff0000, v118
	v_fma_f32 v130, -v186, v13, v110
	v_and_b32_e32 v110, 0xffff0000, v205
	v_fma_f32 v103, -v186, v38, v97
	v_lshlrev_b32_e32 v97, 16, v122
	v_fma_f32 v126, -v186, v22, v110
	v_lshlrev_b32_e32 v110, 16, v208
	v_fma_f32 v100, -v186, v8, v97
	v_and_b32_e32 v97, 0xffff0000, v122
	v_fma_f32 v122, -v186, v14, v110
	v_and_b32_e32 v110, 0xffff0000, v208
	v_fma_f32 v118, -v186, v23, v110
	v_lshlrev_b32_e32 v110, 16, v209
	v_mul_f32_e32 v144, v101, v101
	v_mul_f32_e32 v149, v98, v98
	v_mul_f32_e32 v176, v95, v95
	v_mul_f32_e32 v177, v93, v93
	v_mul_f32_e32 v178, v65, v65
	v_mul_f32_e32 v179, v64, v64
	v_mul_f32_e32 v180, v49, v49
	v_mul_f32_e32 v181, v48, v48
	v_mul_f32_e32 v71, v47, v47
	v_mul_f32_e32 v201, v45, v45
	v_mul_f32_e32 v202, v44, v44
	v_mul_f32_e32 v203, v42, v42
	v_mul_f32_e32 v206, v41, v41
	v_mul_f32_e32 v207, v33, v33
	v_fma_f32 v114, -v186, v15, v110
	v_and_b32_e32 v110, 0xffff0000, v209
	v_fmac_f32_e32 v142, v105, v105
	v_fmac_f32_e32 v143, v102, v102
	v_fmac_f32_e32 v144, v99, v99
	v_fmac_f32_e32 v149, v96, v96
	v_fmac_f32_e32 v176, v94, v94
	v_fmac_f32_e32 v177, v92, v92
	v_fmac_f32_e32 v178, v46, v46
	v_fmac_f32_e32 v179, v43, v43
	v_fmac_f32_e32 v180, v40, v40
	v_fmac_f32_e32 v181, v32, v32
	v_fmac_f32_e32 v71, v31, v31
	v_fmac_f32_e32 v201, v30, v30
	v_fmac_f32_e32 v202, v29, v29
	v_fmac_f32_e32 v203, v28, v28
	v_fmac_f32_e32 v206, v27, v27
	v_fmac_f32_e32 v207, v26, v26
	v_fma_f32 v97, -v186, v39, v97
	v_fma_f32 v112, -v186, v24, v110
	s_waitcnt vmcnt(0)
	v_lshlrev_b32_e32 v110, 16, v107
	v_and_b32_e32 v107, 0xffff0000, v107
	v_fmac_f32_e32 v142, v138, v138
	v_fmac_f32_e32 v143, v136, v136
	v_fmac_f32_e32 v144, v134, v134
	v_fmac_f32_e32 v149, v132, v132
	v_fmac_f32_e32 v176, v131, v131
	v_fmac_f32_e32 v177, v127, v127
	v_fmac_f32_e32 v178, v123, v123
	v_fmac_f32_e32 v179, v119, v119
	v_fmac_f32_e32 v180, v115, v115
	v_fmac_f32_e32 v181, v113, v113
	v_fmac_f32_e32 v71, v111, v111
	v_fmac_f32_e32 v201, v109, v109
	v_fmac_f32_e32 v202, v106, v106
	v_fmac_f32_e32 v203, v103, v103
	v_fmac_f32_e32 v206, v100, v100
	v_fmac_f32_e32 v207, v97, v97
	v_fma_f32 v110, -v186, v16, v110
	v_fma_f32 v107, -v186, v25, v107
	v_fmac_f32_e32 v142, v146, v146
	v_fmac_f32_e32 v143, v145, v145
	v_fmac_f32_e32 v144, v141, v141
	v_fmac_f32_e32 v149, v140, v140
	v_fmac_f32_e32 v176, v139, v139
	v_fmac_f32_e32 v177, v137, v137
	v_fmac_f32_e32 v178, v135, v135
	v_fmac_f32_e32 v179, v133, v133
	v_fmac_f32_e32 v180, v130, v130
	v_fmac_f32_e32 v181, v126, v126
	v_fmac_f32_e32 v71, v122, v122
	v_fmac_f32_e32 v201, v118, v118
	v_fmac_f32_e32 v202, v114, v114
	v_fmac_f32_e32 v203, v112, v112
	v_fmac_f32_e32 v206, v110, v110
	v_fmac_f32_e32 v207, v107, v107
	ds_bpermute_b32 v204, v1, v142
	ds_bpermute_b32 v205, v1, v143
	ds_bpermute_b32 v208, v1, v144
	ds_bpermute_b32 v209, v1, v149
	ds_bpermute_b32 v210, v1, v176
	ds_bpermute_b32 v211, v1, v177
	ds_bpermute_b32 v212, v1, v178
	ds_bpermute_b32 v213, v1, v179
	ds_bpermute_b32 v214, v1, v180
	ds_bpermute_b32 v215, v1, v181
	ds_bpermute_b32 v216, v1, v71
	ds_bpermute_b32 v217, v1, v201
	ds_bpermute_b32 v218, v1, v202
	ds_bpermute_b32 v219, v1, v203
	ds_bpermute_b32 v220, v1, v206
	ds_bpermute_b32 v221, v1, v207
	s_waitcnt lgkmcnt(14)
	v_add_f32_e32 v142, v142, v204
	v_add_f32_e32 v143, v143, v205
	s_waitcnt lgkmcnt(13)
	v_add_f32_e32 v144, v144, v208
	s_waitcnt lgkmcnt(12)
	v_add_f32_e32 v149, v149, v209
	s_waitcnt lgkmcnt(11)
	v_add_f32_e32 v176, v176, v210
	s_waitcnt lgkmcnt(10)
	v_add_f32_e32 v177, v177, v211
	s_waitcnt lgkmcnt(9)
	v_add_f32_e32 v178, v178, v212
	s_waitcnt lgkmcnt(8)
	v_add_f32_e32 v179, v179, v213
	s_waitcnt lgkmcnt(7)
	v_add_f32_e32 v180, v180, v214
	s_waitcnt lgkmcnt(6)
	v_add_f32_e32 v181, v181, v215
	s_waitcnt lgkmcnt(5)
	v_add_f32_e32 v71, v71, v216
	s_waitcnt lgkmcnt(4)
	v_add_f32_e32 v201, v201, v217
	s_waitcnt lgkmcnt(3)
	v_add_f32_e32 v202, v202, v218
	s_waitcnt lgkmcnt(2)
	v_add_f32_e32 v203, v203, v219
	s_waitcnt lgkmcnt(1)
	v_add_f32_e32 v204, v206, v220
	s_waitcnt lgkmcnt(0)
	v_add_f32_e32 v205, v207, v221
	ds_bpermute_b32 v206, v182, v142
	ds_bpermute_b32 v207, v182, v143
	ds_bpermute_b32 v208, v182, v144
	ds_bpermute_b32 v209, v182, v149
	ds_bpermute_b32 v210, v182, v176
	ds_bpermute_b32 v211, v182, v177
	ds_bpermute_b32 v212, v182, v178
	ds_bpermute_b32 v213, v182, v179
	ds_bpermute_b32 v214, v182, v180
	ds_bpermute_b32 v215, v182, v181
	ds_bpermute_b32 v216, v182, v71
	ds_bpermute_b32 v217, v182, v201
	ds_bpermute_b32 v218, v182, v202
	ds_bpermute_b32 v219, v182, v203
	ds_bpermute_b32 v220, v182, v204
	ds_bpermute_b32 v221, v182, v205
	s_waitcnt lgkmcnt(14)
; template <int THRL> ...
;     ...
;       for (int m_ = 1; m_ < 32; m_ <<= 1) {
;         float t_[16];
; #pragma unroll
;         for (int r = 0; r < 16; ++r) t_[r] = __shfl_xor(ss[r], m_);
; #pragma unroll
;         for (int r = 0; r < 16; ++r) ss[r] += t_[r];
;       }
; #pragma unroll
;       for (int r = 0; r < 16; ++r) ss[r] = 0.8f * __builtin_amdgcn_rsqf(ss[r] * (1.0f / 128.0f) + 1e-5f);
;       const unsigned gd_ = need ? __hip_atomic_load(guard, __ATOMIC_RELAXED, __HIP_MEMORY_SCOPE_AGENT) : 0u;
;       float g[4];
; #pragma unroll
;       for (int d0 = 0; d0 < 4; ++d0) g[d0] = subg[d0 * 32 + r32_o];
;       if (gd_ < need) { unsigned sp_ = 0u; while (__hip_atomic_load(guard, __ATOMIC_RELAXED, __HIP_MEMORY_SCOPE_AGENT) < need && ++sp_ < (1u << 22)) __builtin_amdgcn_s_sleep(2); }
	v_add_f32_e32 v142, v142, v206
	v_add_f32_e32 v143, v143, v207
	s_waitcnt lgkmcnt(13)
	v_add_f32_e32 v144, v144, v208
	s_waitcnt lgkmcnt(12)
	v_add_f32_e32 v149, v149, v209
	s_waitcnt lgkmcnt(11)
	v_add_f32_e32 v176, v176, v210
	s_waitcnt lgkmcnt(10)
	v_add_f32_e32 v177, v177, v211
	s_waitcnt lgkmcnt(9)
	v_add_f32_e32 v178, v178, v212
	s_waitcnt lgkmcnt(8)
	v_add_f32_e32 v179, v179, v213
	s_waitcnt lgkmcnt(7)
	v_add_f32_e32 v180, v180, v214
	s_waitcnt lgkmcnt(6)
	v_add_f32_e32 v181, v181, v215
	s_waitcnt lgkmcnt(5)
	v_add_f32_e32 v71, v71, v216
	s_waitcnt lgkmcnt(4)
	v_add_f32_e32 v201, v201, v217
	s_waitcnt lgkmcnt(3)
	v_add_f32_e32 v202, v202, v218
	s_waitcnt lgkmcnt(2)
	v_add_f32_e32 v203, v203, v219
	s_waitcnt lgkmcnt(1)
	v_add_f32_e32 v204, v204, v220
	s_waitcnt lgkmcnt(0)
	v_add_f32_e32 v205, v205, v221
	ds_bpermute_b32 v206, v183, v142
	ds_bpermute_b32 v207, v183, v143
	ds_bpermute_b32 v208, v183, v144
	ds_bpermute_b32 v209, v183, v149
	ds_bpermute_b32 v210, v183, v176
	ds_bpermute_b32 v211, v183, v177
	ds_bpermute_b32 v212, v183, v178
	ds_bpermute_b32 v213, v183, v179
	ds_bpermute_b32 v214, v183, v180
	ds_bpermute_b32 v215, v183, v181
	ds_bpermute_b32 v216, v183, v71
	ds_bpermute_b32 v217, v183, v201
	ds_bpermute_b32 v218, v183, v202
	ds_bpermute_b32 v219, v183, v203
	ds_bpermute_b32 v220, v183, v204
	ds_bpermute_b32 v221, v183, v205
	s_waitcnt lgkmcnt(14)
	v_add_f32_e32 v142, v142, v206
	v_add_f32_e32 v143, v143, v207
	s_waitcnt lgkmcnt(13)
	v_add_f32_e32 v144, v144, v208
	s_waitcnt lgkmcnt(12)
	v_add_f32_e32 v206, v149, v209
	s_waitcnt lgkmcnt(11)
	v_add_f32_e32 v207, v176, v210
	s_waitcnt lgkmcnt(10)
	v_add_f32_e32 v208, v177, v211
	s_waitcnt lgkmcnt(9)
	v_add_f32_e32 v209, v178, v212
	s_waitcnt lgkmcnt(8)
	v_add_f32_e32 v210, v179, v213
	s_waitcnt lgkmcnt(7)
	v_add_f32_e32 v211, v180, v214
	s_waitcnt lgkmcnt(6)
	v_add_f32_e32 v212, v181, v215
	s_waitcnt lgkmcnt(5)
	v_add_f32_e32 v71, v71, v216
	s_waitcnt lgkmcnt(4)
	v_add_f32_e32 v213, v201, v217
	s_waitcnt lgkmcnt(3)
	v_add_f32_e32 v214, v202, v218
	s_waitcnt lgkmcnt(2)
	v_add_f32_e32 v215, v203, v219
	s_waitcnt lgkmcnt(1)
	v_add_f32_e32 v216, v204, v220
	s_waitcnt lgkmcnt(0)
	v_add_f32_e32 v217, v205, v221
	ds_bpermute_b32 v149, v184, v142
	ds_bpermute_b32 v176, v184, v143
	ds_bpermute_b32 v177, v184, v144
	ds_bpermute_b32 v178, v184, v206
	ds_bpermute_b32 v179, v184, v207
	ds_bpermute_b32 v180, v184, v208
	ds_bpermute_b32 v181, v184, v209
	ds_bpermute_b32 v201, v184, v210
	ds_bpermute_b32 v202, v184, v211
	ds_bpermute_b32 v203, v184, v212
	ds_bpermute_b32 v204, v184, v71
	ds_bpermute_b32 v205, v184, v213
	ds_bpermute_b32 v218, v184, v214
	ds_bpermute_b32 v219, v184, v215
	ds_bpermute_b32 v220, v184, v216
	ds_bpermute_b32 v221, v184, v217
	s_waitcnt lgkmcnt(14)
	v_add_f32_e32 v149, v142, v149
	v_add_f32_e32 v176, v143, v176
	s_waitcnt lgkmcnt(13)
	v_add_f32_e32 v177, v144, v177
	s_waitcnt lgkmcnt(12)
	v_add_f32_e32 v178, v206, v178
	s_waitcnt lgkmcnt(11)
	v_add_f32_e32 v179, v207, v179
	s_waitcnt lgkmcnt(10)
	v_add_f32_e32 v180, v208, v180
	s_waitcnt lgkmcnt(9)
	v_add_f32_e32 v181, v209, v181
	s_waitcnt lgkmcnt(8)
	v_add_f32_e32 v201, v210, v201
	s_waitcnt lgkmcnt(7)
	v_add_f32_e32 v202, v211, v202
	s_waitcnt lgkmcnt(6)
	v_add_f32_e32 v203, v212, v203
	s_waitcnt lgkmcnt(5)
	v_add_f32_e32 v204, v71, v204
	s_waitcnt lgkmcnt(4)
	v_add_f32_e32 v205, v213, v205
	s_waitcnt lgkmcnt(3)
	v_add_f32_e32 v206, v214, v218
	s_waitcnt lgkmcnt(2)
	v_add_f32_e32 v207, v215, v219
	s_waitcnt lgkmcnt(1)
	v_add_f32_e32 v208, v216, v220
	s_waitcnt lgkmcnt(0)
	v_add_f32_e32 v209, v217, v221
	ds_bpermute_b32 v210, v185, v149
	ds_bpermute_b32 v211, v185, v176
	ds_bpermute_b32 v212, v185, v177
	ds_bpermute_b32 v213, v185, v178
	ds_bpermute_b32 v214, v185, v179
	ds_bpermute_b32 v215, v185, v180
	ds_bpermute_b32 v216, v185, v181
	ds_bpermute_b32 v217, v185, v201
	ds_bpermute_b32 v218, v185, v202
	ds_bpermute_b32 v219, v185, v203
	ds_bpermute_b32 v220, v185, v204
	ds_bpermute_b32 v221, v185, v205
	ds_bpermute_b32 v222, v185, v206
	ds_bpermute_b32 v223, v185, v207
	ds_bpermute_b32 v224, v185, v208
	ds_bpermute_b32 v225, v185, v209
	s_cbranch_vccnz .LBB0_483
	s_movk_i32 s0, 0x100
	s_waitcnt vmcnt(0)
	v_cmp_gt_u32_e64 s[28:29], s0, v244
.LBB0_483:
	v_ashrrev_i32_e32 v71, 31, v70
	v_lshl_add_u64 v[226:227], v[70:71], 2, s[22:23]
	v_mov_b32_e32 v144, v245
	v_mov_b32_e32 v143, v246
	v_mov_b32_e32 v142, v247
	v_mov_b32_e32 v71, v248
	s_andn2_b64 vcc, exec, s[28:29]
	s_cbranch_vccnz .LBB0_495
	global_load_dword v226, v147, s[12:13] sc1
	s_waitcnt vmcnt(0)
	v_cmp_le_u32_e32 vcc, s42, v226
	s_cbranch_vccnz .LBB0_495
	s_mov_b32 s0, 0x3ffff8
	s_branch .LBB0_487
